# v37 + K-loop: in a tile's true first K-iteration (counter -2 / 0) skip the two vmcnt(8) waits when an epilogue preceded, since its vmcnt(0) already drained the prefetched tiles
# baseline (speedup 1.0000x reference)
; #define PG8_STAGE(bufoff, gbase, voff) do { _Pragma("unroll") for (int _i = 0; _i < 2; ++_i) \
;         __builtin_amdgcn_global_load_lds((const unsigned*)((const char*)(gbase) + (voff)[_i]), (PG8_LAS unsigned*)(lds + (bufoff) + ldsw + _i * 8192), 16, 0, 0); } while (0)
; #define PG8_LDA(dst, b, h) do { _Pragma("unroll") for (int m = 0; m < 4; ++m) _Pragma("unroll") for (int k = 0; k < 2; ++k) dst[m][k] = *(const PG8_LAS bf16x8*)(lds + PG8_SA(b, h) + aoff + m * 2048 + k * 1024); } while (0)
; #define PG8_LDB(dst, b, h) do { _Pragma("unroll") for (int n = 0; n < 2; ++n) _Pragma("unroll") for (int k = 0; k < 2; ++k) dst[n][k] = *(const PG8_LAS bf16x8*)(lds + PG8_SB(b, h) + boff + n * 2048 + k * 1024); } while (0)
; #define PG8_MMA(ai, bj, At, Bt) do { __builtin_amdgcn_s_setprio(1); _Pragma("unroll") for (int m = 0; m < 4; ++m) _Pragma("unroll") for (int n = 0; n < 2; ++n) _Pragma("unroll") for (int k = 0; k < 2; ++k) \
;         acc[ai][bj][m][n] = __builtin_amdgcn_mfma_f32_16x16x32_bf16(Bt[n][k], At[m][k], acc[ai][bj][m][n], 0, 0, 0); __builtin_amdgcn_s_setprio(0); } while (0)
; #define PG8_WAIT_V(n) asm volatile("s_waitcnt vmcnt(" #n ")" ::: "memory")
; #define PG8_WAIT_L(n) asm volatile("s_waitcnt lgkmcnt(" #n ")" ::: "memory")
; #define PG8_BAR __builtin_amdgcn_s_barrier()
; #define PG8_SCHED __builtin_amdgcn_sched_barrier(0)
; template <class Epi, class Sched, bool ALIGN_EPI = false, bool SP2 = false>
; __device__ __forceinline__ void gemm_phase(PG8_LAS unsigned char* lds, const Gemm g, const Sched& S, const Epi& E, const int tid_in) {
;     ...
;             PG8_LDB(B0, 0, 0); PG8_LDB(B1, 0, 1); PG8_SCHED; PG8_LDA(At, 0, 0); PG8_STAGE(PG8_SA(1, 1), a1 + hstep, voffA);
;             PG8_WAIT_V(8); PG8_WAIT_L(0); PG8_BAR; PG8_MMA(0, 0, At, B0); PG8_MMA(0, 1, At, B1); PG8_BAR; PG8_SCHED;
;             PG8_LDA(At, 0, 1); PG8_STAGE(PG8_SB(0, 0), b2, voffB); PG8_STAGE(PG8_SB(0, 1), b2 + hstep, voffB); PG8_STAGE(PG8_SA(0, 0), a2, voffA);
;             PG8_WAIT_V(8); PG8_WAIT_L(0); PG8_BAR; PG8_MMA(1, 0, At, B0); PG8_MMA(1, 1, At, B1); PG8_BAR; PG8_SCHED;
.LBB0_197:
	s_add_u32 s51, s40, 0xfffc0080
	s_addc_u32 s56, s41, -1
	s_add_i32 s88, 0, 0x10000
	s_cmp_eq_u32 s49, 12
	s_cselect_b32 s59, s9, s56
	s_cselect_b32 s58, s16, s51
	s_cselect_b32 s57, s17, s39
	s_cselect_b32 s56, s20, s21
	s_add_i32 s51, 0, 0x14000
	v_add_u32_e32 v44, s88, v178
	v_add_u32_e32 v158, s51, v178
	ds_read_b128 v[24:27], v44
	ds_read_b128 v[28:31], v44 offset:1024
	ds_read_b128 v[40:43], v44 offset:2048
	ds_read_b128 v[44:47], v44 offset:3072
	ds_read_b128 v[154:157], v158
	ds_read_b128 v[182:185], v158 offset:1024
	ds_read_b128 v[186:189], v158 offset:2048
	ds_read_b128 v[190:193], v158 offset:3072
	v_lshl_add_u64 v[158:159], s[40:41], 0, v[150:151]
	s_add_i32 m0, s60, 0xc000
	ds_read_b128 v[194:197], v180
	ds_read_b128 v[198:201], v180 offset:1024
	ds_read_b128 v[202:205], v180 offset:2048
	ds_read_b128 v[206:209], v180 offset:3072
	ds_read_b128 v[210:213], v180 offset:4096
	ds_read_b128 v[214:217], v180 offset:5120
	ds_read_b128 v[218:221], v180 offset:6144
	ds_read_b128 v[238:241], v180 offset:7168
	global_load_lds_dwordx4 v[158:159], off
	v_lshl_add_u64 v[158:159], s[40:41], 0, v[152:153]
	s_add_i32 m0, s60, 0xe000
	s_nop 0
	global_load_lds_dwordx4 v[158:159], off
	s_cmp_eq_i32 s49, -2
	s_cselect_b32 s101, s100, 0
	s_cmp_lg_u32 s101, 0
	s_cbranch_scc1 .Lskipw_p_0
	s_waitcnt vmcnt(8)
.Lskipw_p_0:
	s_waitcnt lgkmcnt(0)
	s_barrier
	s_setprio 1
	s_waitcnt lgkmcnt(0)
	v_mfma_f32_16x16x32_bf16 v[140:143], v[24:27], v[194:197], v[140:143]
	v_mfma_f32_16x16x32_bf16 v[136:139], v[40:43], v[194:197], v[136:139]
	v_mfma_f32_16x16x32_bf16 v[124:127], v[24:27], v[202:205], v[124:127]
	v_mfma_f32_16x16x32_bf16 v[120:123], v[40:43], v[202:205], v[120:123]
	v_mfma_f32_16x16x32_bf16 v[108:111], v[24:27], v[210:213], v[108:111]
	v_mfma_f32_16x16x32_bf16 v[104:107], v[40:43], v[210:213], v[104:107]
	v_mfma_f32_16x16x32_bf16 v[92:95], v[24:27], v[218:221], v[92:95]
	v_mfma_f32_16x16x32_bf16 v[88:91], v[40:43], v[218:221], v[88:91]
	v_mfma_f32_16x16x32_bf16 v[140:143], v[28:31], v[198:201], v[140:143]
	v_mfma_f32_16x16x32_bf16 v[136:139], v[44:47], v[198:201], v[136:139]
	v_mfma_f32_16x16x32_bf16 v[124:127], v[28:31], v[206:209], v[124:127]
	v_mfma_f32_16x16x32_bf16 v[120:123], v[44:47], v[206:209], v[120:123]
	v_mfma_f32_16x16x32_bf16 v[108:111], v[28:31], v[214:217], v[108:111]
	v_mfma_f32_16x16x32_bf16 v[104:107], v[44:47], v[214:217], v[104:107]
	v_mfma_f32_16x16x32_bf16 v[92:95], v[28:31], v[238:241], v[92:95]
	v_mfma_f32_16x16x32_bf16 v[88:91], v[44:47], v[238:241], v[88:91]
	s_setprio 0
	s_setprio 1
	v_mfma_f32_16x16x32_bf16 v[132:135], v[154:157], v[194:197], v[132:135]
	v_mfma_f32_16x16x32_bf16 v[128:131], v[186:189], v[194:197], v[128:131]
	v_mfma_f32_16x16x32_bf16 v[116:119], v[154:157], v[202:205], v[116:119]
	v_mfma_f32_16x16x32_bf16 v[112:115], v[186:189], v[202:205], v[112:115]
	v_mfma_f32_16x16x32_bf16 v[100:103], v[154:157], v[210:213], v[100:103]
	v_mfma_f32_16x16x32_bf16 v[96:99], v[186:189], v[210:213], v[96:99]
	v_mfma_f32_16x16x32_bf16 v[84:87], v[154:157], v[218:221], v[84:87]
	v_mfma_f32_16x16x32_bf16 v[80:83], v[186:189], v[218:221], v[80:83]
	v_mfma_f32_16x16x32_bf16 v[132:135], v[182:185], v[198:201], v[132:135]
	v_mfma_f32_16x16x32_bf16 v[128:131], v[190:193], v[198:201], v[128:131]
	v_mfma_f32_16x16x32_bf16 v[116:119], v[182:185], v[206:209], v[116:119]
	v_mfma_f32_16x16x32_bf16 v[112:115], v[190:193], v[206:209], v[112:115]
	v_mfma_f32_16x16x32_bf16 v[100:103], v[182:185], v[214:217], v[100:103]
	v_mfma_f32_16x16x32_bf16 v[96:99], v[190:193], v[214:217], v[96:99]
	v_mfma_f32_16x16x32_bf16 v[84:87], v[182:185], v[238:241], v[84:87]
	v_mfma_f32_16x16x32_bf16 v[80:83], v[190:193], v[238:241], v[80:83]
	s_setprio 0
	s_barrier
	s_add_i32 s88, s88, s29
	v_lshl_add_u64 v[158:159], s[56:57], 0, v[160:161]
	s_mov_b32 m0, s88
	ds_read_b128 v[194:197], v180 offset:16384
	ds_read_b128 v[198:201], v180 offset:17408
	ds_read_b128 v[202:205], v180 offset:18432
	ds_read_b128 v[206:209], v180 offset:19456
	ds_read_b128 v[210:213], v180 offset:20480
	ds_read_b128 v[214:217], v180 offset:21504
	ds_read_b128 v[218:221], v180 offset:22528
	ds_read_b128 v[238:241], v180 offset:23552
	global_load_lds_dwordx4 v[158:159], off
	s_add_i32 m0, s88, 0x2000
	s_add_u32 s88, s56, 0x40000
	v_lshl_add_u64 v[176:177], s[56:57], 0, v[144:145]
	s_addc_u32 s89, s57, 0
	s_add_i32 s51, s51, s29
	global_load_lds_dwordx4 v[176:177], off
	v_lshl_add_u64 v[242:243], s[88:89], 0, v[160:161]
	s_mov_b32 m0, s51
	v_lshl_add_u64 v[244:245], s[58:59], 0, v[146:147]
	global_load_lds_dwordx4 v[242:243], off
	v_lshl_add_u64 v[242:243], s[88:89], 0, v[144:145]
	s_add_i32 m0, s51, 0x2000
	s_nop 0
	global_load_lds_dwordx4 v[242:243], off
	v_lshl_add_u64 v[242:243], s[58:59], 0, v[148:149]
	s_mov_b32 m0, s60
	s_nop 0
	global_load_lds_dwordx4 v[242:243], off
	s_mov_b32 m0, s61
	s_nop 0
	global_load_lds_dwordx4 v[244:245], off
	s_cmp_eq_i32 s49, -2
	s_cselect_b32 s101, s100, 0
	s_cmp_lg_u32 s101, 0
	s_cbranch_scc1 .Lskipw_p_1
	s_waitcnt vmcnt(8)

; #define PG8_STAGE(bufoff, gbase, voff) do { _Pragma("unroll") for (int _i = 0; _i < 2; ++_i) \
;         __builtin_amdgcn_global_load_lds((const unsigned*)((const char*)(gbase) + (voff)[_i]), (PG8_LAS unsigned*)(lds + (bufoff) + ldsw + _i * 8192), 16, 0, 0); } while (0)
; #define PG8_LDA(dst, b, h) do { _Pragma("unroll") for (int m = 0; m < 4; ++m) _Pragma("unroll") for (int k = 0; k < 2; ++k) dst[m][k] = *(const PG8_LAS bf16x8*)(lds + PG8_SA(b, h) + aoff + m * 2048 + k * 1024); } while (0)
; #define PG8_LDB(dst, b, h) do { _Pragma("unroll") for (int n = 0; n < 2; ++n) _Pragma("unroll") for (int k = 0; k < 2; ++k) dst[n][k] = *(const PG8_LAS bf16x8*)(lds + PG8_SB(b, h) + boff + n * 2048 + k * 1024); } while (0)
; #define PG8_MMA(ai, bj, At, Bt) do { __builtin_amdgcn_s_setprio(1); _Pragma("unroll") for (int m = 0; m < 4; ++m) _Pragma("unroll") for (int n = 0; n < 2; ++n) _Pragma("unroll") for (int k = 0; k < 2; ++k) \
;         acc[ai][bj][m][n] = __builtin_amdgcn_mfma_f32_16x16x32_bf16(Bt[n][k], At[m][k], acc[ai][bj][m][n], 0, 0, 0); __builtin_amdgcn_s_setprio(0); } while (0)
; #define PG8_WAIT_V(n) asm volatile("s_waitcnt vmcnt(" #n ")" ::: "memory")
; #define PG8_WAIT_L(n) asm volatile("s_waitcnt lgkmcnt(" #n ")" ::: "memory")
; #define PG8_BAR __builtin_amdgcn_s_barrier()
; #define PG8_SCHED __builtin_amdgcn_sched_barrier(0)
; template <class Epi, class Sched, bool ALIGN_EPI = false, bool SP2 = false>
; __device__ __forceinline__ void gemm_phase(PG8_LAS unsigned char* lds, const Gemm g, const Sched& S, const Epi& E, const int tid_in) {
;     ...
;             PG8_LDB(B0, 0, 0); PG8_LDB(B1, 0, 1); PG8_SCHED; PG8_LDA(At, 0, 0); PG8_STAGE(PG8_SA(1, 1), a1 + hstep, voffA);
;             PG8_WAIT_V(8); PG8_WAIT_L(0); PG8_BAR; PG8_MMA(0, 0, At, B0); PG8_MMA(0, 1, At, B1); PG8_BAR; PG8_SCHED;
;             PG8_LDA(At, 0, 1); PG8_STAGE(PG8_SB(0, 0), b2, voffB); PG8_STAGE(PG8_SB(0, 1), b2 + hstep, voffB); PG8_STAGE(PG8_SA(0, 0), a2, voffA);
;             PG8_WAIT_V(8); PG8_WAIT_L(0); PG8_BAR; PG8_MMA(1, 0, At, B0); PG8_MMA(1, 1, At, B1); PG8_BAR; PG8_SCHED;
.LBB0_322:
	s_add_i32 s65, s46, 2
	s_add_u32 vcc_lo, s40, 0x80
	s_addc_u32 s47, s41, 0
	s_add_i32 s10, 0, 0x10000
	s_cmp_eq_u32 s93, s46
	s_cselect_b32 s47, s61, s47
	s_cselect_b32 s46, s60, vcc_lo
	s_cselect_b32 vcc_hi, s63, s64
	s_cselect_b32 vcc_lo, s62, s21
	s_add_i32 s11, 0, 0x14000
	v_add_u32_e32 v140, s10, v237
	v_add_u32_e32 v156, s11, v237
	ds_read_b128 v[128:131], v140
	ds_read_b128 v[132:135], v140 offset:1024
	ds_read_b128 v[136:139], v140 offset:2048
	ds_read_b128 v[140:143], v140 offset:3072
	ds_read_b128 v[144:147], v156
	ds_read_b128 v[148:151], v156 offset:1024
	ds_read_b128 v[152:155], v156 offset:2048
	ds_read_b128 v[156:159], v156 offset:3072
	v_lshl_add_u64 v[240:241], s[40:41], 0, v[186:187]
	s_add_i32 m0, s88, 0xc000
	ds_read_b128 v[190:193], v239
	ds_read_b128 v[194:197], v239 offset:1024
	ds_read_b128 v[198:201], v239 offset:2048
	ds_read_b128 v[202:205], v239 offset:3072
	ds_read_b128 v[206:209], v239 offset:4096
	ds_read_b128 v[210:213], v239 offset:5120
	ds_read_b128 v[214:217], v239 offset:6144
	ds_read_b128 v[218:221], v239 offset:7168
	global_load_lds_dwordx4 v[240:241], off
	v_lshl_add_u64 v[240:241], s[40:41], 0, v[188:189]
	s_add_i32 m0, s88, 0xe000
	s_nop 0
	global_load_lds_dwordx4 v[240:241], off
	s_cmp_eq_i32 s65, 2
	s_cselect_b32 s101, s100, 0
	s_cmp_lg_u32 s101, 0
	s_cbranch_scc1 .Lskipw_r_0
	s_waitcnt vmcnt(8)
.Lskipw_r_0:
	s_waitcnt lgkmcnt(0)
	s_barrier
	s_setprio 1
	s_waitcnt lgkmcnt(0)
	v_mfma_f32_16x16x32_bf16 v[124:127], v[128:131], v[190:193], v[124:127]
	v_mfma_f32_16x16x32_bf16 v[120:123], v[136:139], v[190:193], v[120:123]
	v_mfma_f32_16x16x32_bf16 v[108:111], v[128:131], v[198:201], v[108:111]
	v_mfma_f32_16x16x32_bf16 v[104:107], v[136:139], v[198:201], v[104:107]
	v_mfma_f32_16x16x32_bf16 v[92:95], v[128:131], v[206:209], v[92:95]
	v_mfma_f32_16x16x32_bf16 v[88:91], v[136:139], v[206:209], v[88:91]
	v_mfma_f32_16x16x32_bf16 v[76:79], v[128:131], v[214:217], v[76:79]
	v_mfma_f32_16x16x32_bf16 v[72:75], v[136:139], v[214:217], v[72:75]
	v_mfma_f32_16x16x32_bf16 v[124:127], v[132:135], v[194:197], v[124:127]
	v_mfma_f32_16x16x32_bf16 v[120:123], v[140:143], v[194:197], v[120:123]
	v_mfma_f32_16x16x32_bf16 v[108:111], v[132:135], v[202:205], v[108:111]
	v_mfma_f32_16x16x32_bf16 v[104:107], v[140:143], v[202:205], v[104:107]
	v_mfma_f32_16x16x32_bf16 v[92:95], v[132:135], v[210:213], v[92:95]
	v_mfma_f32_16x16x32_bf16 v[88:91], v[140:143], v[210:213], v[88:91]
	v_mfma_f32_16x16x32_bf16 v[76:79], v[132:135], v[218:221], v[76:79]
	v_mfma_f32_16x16x32_bf16 v[72:75], v[140:143], v[218:221], v[72:75]
	s_setprio 0
	s_setprio 1
	v_mfma_f32_16x16x32_bf16 v[116:119], v[144:147], v[190:193], v[116:119]
	v_mfma_f32_16x16x32_bf16 v[112:115], v[152:155], v[190:193], v[112:115]
	v_mfma_f32_16x16x32_bf16 v[100:103], v[144:147], v[198:201], v[100:103]
	v_mfma_f32_16x16x32_bf16 v[96:99], v[152:155], v[198:201], v[96:99]
	v_mfma_f32_16x16x32_bf16 v[84:87], v[144:147], v[206:209], v[84:87]
	v_mfma_f32_16x16x32_bf16 v[80:83], v[152:155], v[206:209], v[80:83]
	v_mfma_f32_16x16x32_bf16 v[68:71], v[144:147], v[214:217], v[68:71]
	v_mfma_f32_16x16x32_bf16 v[64:67], v[152:155], v[214:217], v[64:67]
	v_mfma_f32_16x16x32_bf16 v[116:119], v[148:151], v[194:197], v[116:119]
	v_mfma_f32_16x16x32_bf16 v[112:115], v[156:159], v[194:197], v[112:115]
	v_mfma_f32_16x16x32_bf16 v[100:103], v[148:151], v[202:205], v[100:103]
	v_mfma_f32_16x16x32_bf16 v[96:99], v[156:159], v[202:205], v[96:99]
	v_mfma_f32_16x16x32_bf16 v[84:87], v[148:151], v[210:213], v[84:87]
	v_mfma_f32_16x16x32_bf16 v[80:83], v[156:159], v[210:213], v[80:83]
	v_mfma_f32_16x16x32_bf16 v[68:71], v[148:151], v[218:221], v[68:71]
	v_mfma_f32_16x16x32_bf16 v[64:67], v[156:159], v[218:221], v[64:67]
	s_setprio 0
	s_barrier
	s_add_i32 s10, s10, s87
	v_lshl_add_u64 v[240:241], vcc, 0, v[160:161]
	s_mov_b32 m0, s10
	ds_read_b128 v[190:193], v239 offset:16384
	ds_read_b128 v[194:197], v239 offset:17408
	ds_read_b128 v[198:201], v239 offset:18432
	ds_read_b128 v[202:205], v239 offset:19456
	ds_read_b128 v[206:209], v239 offset:20480
	ds_read_b128 v[210:213], v239 offset:21504
	ds_read_b128 v[214:217], v239 offset:22528
	ds_read_b128 v[218:221], v239 offset:23552
	global_load_lds_dwordx4 v[240:241], off
	s_add_i32 m0, s10, 0x2000
	v_lshl_add_u64 v[242:243], vcc, 0, v[176:177]
	s_add_u32 vcc_lo, vcc_lo, s22
	s_addc_u32 vcc_hi, vcc_hi, 0
	s_add_i32 s10, s11, s87
	global_load_lds_dwordx4 v[242:243], off
	v_lshl_add_u64 v[244:245], vcc, 0, v[160:161]
	s_mov_b32 m0, s10
	v_lshl_add_u64 v[246:247], vcc, 0, v[176:177]
	global_load_lds_dwordx4 v[244:245], off
	s_add_i32 m0, s10, 0x2000
	v_lshl_add_u64 v[248:249], s[46:47], 0, v[180:181]
	global_load_lds_dwordx4 v[246:247], off
	s_mov_b32 m0, s88
	v_lshl_add_u64 v[250:251], s[46:47], 0, v[178:179]
	global_load_lds_dwordx4 v[248:249], off
	s_mov_b32 m0, s89
	s_nop 0
	global_load_lds_dwordx4 v[250:251], off
	s_cmp_eq_i32 s65, 2
	s_cselect_b32 s101, s100, 0
	s_cmp_lg_u32 s101, 0
	s_cbranch_scc1 .Lskipw_r_1
	s_waitcnt vmcnt(8)

; #define PG8_STAGE(bufoff, gbase, voff) do { _Pragma("unroll") for (int _i = 0; _i < 2; ++_i) \
;         __builtin_amdgcn_global_load_lds((const unsigned*)((const char*)(gbase) + (voff)[_i]), (PG8_LAS unsigned*)(lds + (bufoff) + ldsw + _i * 8192), 16, 0, 0); } while (0)
; #define PG8_LDA(dst, b, h) do { _Pragma("unroll") for (int m = 0; m < 4; ++m) _Pragma("unroll") for (int k = 0; k < 2; ++k) dst[m][k] = *(const PG8_LAS bf16x8*)(lds + PG8_SA(b, h) + aoff + m * 2048 + k * 1024); } while (0)
; #define PG8_LDB(dst, b, h) do { _Pragma("unroll") for (int n = 0; n < 2; ++n) _Pragma("unroll") for (int k = 0; k < 2; ++k) dst[n][k] = *(const PG8_LAS bf16x8*)(lds + PG8_SB(b, h) + boff + n * 2048 + k * 1024); } while (0)
; #define PG8_MMA(ai, bj, At, Bt) do { __builtin_amdgcn_s_setprio(1); _Pragma("unroll") for (int m = 0; m < 4; ++m) _Pragma("unroll") for (int n = 0; n < 2; ++n) _Pragma("unroll") for (int k = 0; k < 2; ++k) \
;         acc[ai][bj][m][n] = __builtin_amdgcn_mfma_f32_16x16x32_bf16(Bt[n][k], At[m][k], acc[ai][bj][m][n], 0, 0, 0); __builtin_amdgcn_s_setprio(0); } while (0)
; #define PG8_WAIT_V(n) asm volatile("s_waitcnt vmcnt(" #n ")" ::: "memory")
; #define PG8_WAIT_L(n) asm volatile("s_waitcnt lgkmcnt(" #n ")" ::: "memory")
; #define PG8_BAR __builtin_amdgcn_s_barrier()
; #define PG8_SCHED __builtin_amdgcn_sched_barrier(0)
; template <class Epi, class Sched, bool ALIGN_EPI = false, bool SP2 = false>
; __device__ __forceinline__ void gemm_phase(PG8_LAS unsigned char* lds, const Gemm g, const Sched& S, const Epi& E, const int tid_in) {
;     ...
;             PG8_LDB(B0, 0, 0); PG8_LDB(B1, 0, 1); PG8_SCHED; PG8_LDA(At, 0, 0); PG8_STAGE(PG8_SA(1, 1), a1 + hstep, voffA);
;             PG8_WAIT_V(8); PG8_WAIT_L(0); PG8_BAR; PG8_MMA(0, 0, At, B0); PG8_MMA(0, 1, At, B1); PG8_BAR; PG8_SCHED;
;             PG8_LDA(At, 0, 1); PG8_STAGE(PG8_SB(0, 0), b2, voffB); PG8_STAGE(PG8_SB(0, 1), b2 + hstep, voffB); PG8_STAGE(PG8_SA(0, 0), a2, voffA);
;             PG8_WAIT_V(8); PG8_WAIT_L(0); PG8_BAR; PG8_MMA(1, 0, At, B0); PG8_MMA(1, 1, At, B1); PG8_BAR; PG8_SCHED;
.LBB0_400:
	s_add_u32 s52, s40, 0xfffc0080
	s_addc_u32 s53, s41, -1
	s_add_i32 s87, 0, 0x10000
	s_cmp_eq_u32 s47, 12
	s_cselect_b32 s55, s9, s53
	s_cselect_b32 s54, s16, s52
	s_cselect_b32 s53, s17, s45
	s_cselect_b32 s52, s20, s21
	s_add_i32 s90, 0, 0x14000
	v_add_u32_e32 v60, s87, v180
	v_add_u32_e32 v158, s90, v180
	ds_read_b128 v[48:51], v60
	ds_read_b128 v[52:55], v60 offset:1024
	ds_read_b128 v[56:59], v60 offset:2048
	ds_read_b128 v[60:63], v60 offset:3072
	ds_read_b128 v[154:157], v158
	ds_read_b128 v[176:179], v158 offset:1024
	ds_read_b128 v[184:187], v158 offset:2048
	ds_read_b128 v[188:191], v158 offset:3072
	v_lshl_add_u64 v[158:159], s[40:41], 0, v[150:151]
	s_add_i32 m0, s58, 0xc000
	ds_read_b128 v[192:195], v182
	ds_read_b128 v[196:199], v182 offset:1024
	ds_read_b128 v[200:203], v182 offset:2048
	ds_read_b128 v[204:207], v182 offset:3072
	ds_read_b128 v[208:211], v182 offset:4096
	ds_read_b128 v[212:215], v182 offset:5120
	ds_read_b128 v[216:219], v182 offset:6144
	ds_read_b128 v[238:241], v182 offset:7168
	global_load_lds_dwordx4 v[158:159], off
	v_lshl_add_u64 v[158:159], s[40:41], 0, v[152:153]
	s_add_i32 m0, s58, 0xe000
	s_nop 0
	global_load_lds_dwordx4 v[158:159], off
	s_cmp_eq_i32 s47, -2
	s_cselect_b32 s101, s100, 0
	s_cmp_lg_u32 s101, 0
	s_cbranch_scc1 .Lskipw_s_0
	s_waitcnt vmcnt(8)
.Lskipw_s_0:
	s_waitcnt lgkmcnt(0)
	s_barrier
	s_setprio 1
	s_waitcnt lgkmcnt(0)
	v_mfma_f32_16x16x32_bf16 v[140:143], v[48:51], v[192:195], v[140:143]
	v_mfma_f32_16x16x32_bf16 v[136:139], v[56:59], v[192:195], v[136:139]
	v_mfma_f32_16x16x32_bf16 v[124:127], v[48:51], v[200:203], v[124:127]
	v_mfma_f32_16x16x32_bf16 v[120:123], v[56:59], v[200:203], v[120:123]
	v_mfma_f32_16x16x32_bf16 v[108:111], v[48:51], v[208:211], v[108:111]
	v_mfma_f32_16x16x32_bf16 v[104:107], v[56:59], v[208:211], v[104:107]
	v_mfma_f32_16x16x32_bf16 v[92:95], v[48:51], v[216:219], v[92:95]
	v_mfma_f32_16x16x32_bf16 v[88:91], v[56:59], v[216:219], v[88:91]
	v_mfma_f32_16x16x32_bf16 v[140:143], v[52:55], v[196:199], v[140:143]
	v_mfma_f32_16x16x32_bf16 v[136:139], v[60:63], v[196:199], v[136:139]
	v_mfma_f32_16x16x32_bf16 v[124:127], v[52:55], v[204:207], v[124:127]
	v_mfma_f32_16x16x32_bf16 v[120:123], v[60:63], v[204:207], v[120:123]
	v_mfma_f32_16x16x32_bf16 v[108:111], v[52:55], v[212:215], v[108:111]
	v_mfma_f32_16x16x32_bf16 v[104:107], v[60:63], v[212:215], v[104:107]
	v_mfma_f32_16x16x32_bf16 v[92:95], v[52:55], v[238:241], v[92:95]
	v_mfma_f32_16x16x32_bf16 v[88:91], v[60:63], v[238:241], v[88:91]
	s_setprio 0
	s_setprio 1
	v_mfma_f32_16x16x32_bf16 v[132:135], v[154:157], v[192:195], v[132:135]
	v_mfma_f32_16x16x32_bf16 v[128:131], v[184:187], v[192:195], v[128:131]
	v_mfma_f32_16x16x32_bf16 v[116:119], v[154:157], v[200:203], v[116:119]
	v_mfma_f32_16x16x32_bf16 v[112:115], v[184:187], v[200:203], v[112:115]
	v_mfma_f32_16x16x32_bf16 v[100:103], v[154:157], v[208:211], v[100:103]
	v_mfma_f32_16x16x32_bf16 v[96:99], v[184:187], v[208:211], v[96:99]
	v_mfma_f32_16x16x32_bf16 v[84:87], v[154:157], v[216:219], v[84:87]
	v_mfma_f32_16x16x32_bf16 v[80:83], v[184:187], v[216:219], v[80:83]
	v_mfma_f32_16x16x32_bf16 v[132:135], v[176:179], v[196:199], v[132:135]
	v_mfma_f32_16x16x32_bf16 v[128:131], v[188:191], v[196:199], v[128:131]
	v_mfma_f32_16x16x32_bf16 v[116:119], v[176:179], v[204:207], v[116:119]
	v_mfma_f32_16x16x32_bf16 v[112:115], v[188:191], v[204:207], v[112:115]
	v_mfma_f32_16x16x32_bf16 v[100:103], v[176:179], v[212:215], v[100:103]
	v_mfma_f32_16x16x32_bf16 v[96:99], v[188:191], v[212:215], v[96:99]
	v_mfma_f32_16x16x32_bf16 v[84:87], v[176:179], v[238:241], v[84:87]
	v_mfma_f32_16x16x32_bf16 v[80:83], v[188:191], v[238:241], v[80:83]
	s_setprio 0
	s_barrier
	s_add_i32 s87, s87, s57
	v_lshl_add_u64 v[158:159], s[52:53], 0, v[160:161]
	s_mov_b32 m0, s87
	ds_read_b128 v[192:195], v182 offset:16384
	ds_read_b128 v[196:199], v182 offset:17408
	ds_read_b128 v[200:203], v182 offset:18432
	ds_read_b128 v[204:207], v182 offset:19456
	ds_read_b128 v[208:211], v182 offset:20480
	ds_read_b128 v[212:215], v182 offset:21504
	ds_read_b128 v[216:219], v182 offset:22528
	ds_read_b128 v[238:241], v182 offset:23552
	global_load_lds_dwordx4 v[158:159], off
	s_add_i32 m0, s87, 0x2000
	s_add_u32 s88, s52, 0x40000
	v_lshl_add_u64 v[220:221], s[52:53], 0, v[144:145]
	s_addc_u32 s89, s53, 0
	s_add_i32 s87, s90, s57
	global_load_lds_dwordx4 v[220:221], off
	v_lshl_add_u64 v[242:243], s[88:89], 0, v[160:161]
	s_mov_b32 m0, s87
	v_lshl_add_u64 v[244:245], s[54:55], 0, v[146:147]
	global_load_lds_dwordx4 v[242:243], off
	v_lshl_add_u64 v[242:243], s[88:89], 0, v[144:145]
	s_add_i32 m0, s87, 0x2000
	s_nop 0
	global_load_lds_dwordx4 v[242:243], off
	v_lshl_add_u64 v[242:243], s[54:55], 0, v[148:149]
	s_mov_b32 m0, s58
	s_nop 0
	global_load_lds_dwordx4 v[242:243], off
	s_mov_b32 m0, s59
	s_nop 0
	global_load_lds_dwordx4 v[244:245], off
	s_cmp_eq_i32 s47, -2
	s_cselect_b32 s101, s100, 0
	s_cmp_lg_u32 s101, 0
	s_cbranch_scc1 .Lskipw_s_1
	s_waitcnt vmcnt(8)
